# v045 + P11 loop back-edge pointer updates hoisted in front of the closing barrier
# speedup vs baseline: 1.0047x; 1.0047x over previous
; #define PG8_STAGE(bufoff, gbase, voff) do { _Pragma("unroll") for (int _i = 0; _i < 2; ++_i) \
;         __builtin_amdgcn_global_load_lds((const unsigned*)((const char*)(gbase) + (voff)[_i]), (LAS unsigned*)(lds + (bufoff) + ldsw + _i * 8192), 16, 0, 0); } while (0)
; #define PG8_LDA(dst, b, h) do { _Pragma("unroll") for (int m = 0; m < 4; ++m) _Pragma("unroll") for (int k = 0; k < 2; ++k) dst[m][k] = *(const LAS bf16x8*)(lds + PG8_SA(b, h) + aoff + m * 2048 + k * 1024); } while (0)
; #define PG8_LDB(dst, b, h) do { _Pragma("unroll") for (int n = 0; n < 2; ++n) _Pragma("unroll") for (int k = 0; k < 2; ++k) dst[n][k] = *(const LAS bf16x8*)(lds + PG8_SB(b, h) + boff + n * 2048 + k * 1024); } while (0)
; #define PG8_MMA(ai, bj, At, Bt) do { __builtin_amdgcn_s_setprio(1); _Pragma("unroll") for (int m = 0; m < 4; ++m) _Pragma("unroll") for (int n = 0; n < 2; ++n) _Pragma("unroll") for (int k = 0; k < 2; ++k) \
;         acc[ai][bj][m][n] = __builtin_amdgcn_mfma_f32_16x16x32_bf16(Bt[n][k], At[m][k], acc[ai][bj][m][n], 0, 0, 0); __builtin_amdgcn_s_setprio(0); } while (0)
; #define PG8_WAIT_V(n) asm volatile("s_waitcnt vmcnt(" #n ")" ::: "memory")
; #define PG8_WAIT_L(n) asm volatile("s_waitcnt lgkmcnt(" #n ")" ::: "memory")
; template <class Epi, class Sched, bool ALIGN_EPI = false, bool SP2 = false>
; __device__ __forceinline__ void gemm_phase(LAS unsigned char* lds, const Gemm g, const Sched& S, const Epi& E) {
;     ...
;         for (int t = 0; t < nt; t += 2) {
;             const bool last = (t == nt - 2);
;             const char* a1 = cA + (size_t)(t + 1) * kstep;
;             const char* a2 = last ? nA : cA + (size_t)(t + 2) * kstep; const char* b2 = last ? nB : cB + (size_t)(t + 2) * kstep;
;             const char* a3 = a2 + kstep; const char* b3 = b2 + kstep;
;             if (last && has_next) S.a_ready(nxt);
;             if constexpr (SP2) {
;             PG8_LDB(B0, 0, 0); PG8_LDB(B1, 0, 1); PG8_SCHED; PG8_LDA(At, 0, 0); PG8_STAGE(PG8_SA(1, 1), a1 + hstepA, voffA);
;             PG8_WAIT_V(8); PG8_WAIT_L(0); PG8_BAR; PG8_MMA(0, 0, At, B0); PG8_MMA(0, 1, At, B1); PG8_BAR; PG8_SCHED;
;             PG8_LDA(At, 0, 1); PG8_STAGE(PG8_SB(0, 0), b2, voffB); PG8_STAGE(PG8_SB(0, 1), b2 + hstepB, voffB); PG8_STAGE(PG8_SA(0, 0), a2, voffA);
;             PG8_WAIT_V(8); PG8_WAIT_L(0); PG8_BAR; PG8_MMA(1, 0, At, B0); PG8_MMA(1, 1, At, B1); PG8_BAR; PG8_SCHED;
.LBB0_1138:
	ds_read_b128 v[128:131], v176
	ds_read_b128 v[132:135], v176 offset:1024
	ds_read_b128 v[152:155], v176 offset:2048
	ds_read_b128 v[156:159], v176 offset:3072
	ds_read_b128 v[160:163], v177
	ds_read_b128 v[164:167], v177 offset:1024
	ds_read_b128 v[168:171], v177 offset:2048
	ds_read_b128 v[182:185], v177 offset:3072
	s_add_u32 s22, s20, 0xffea0080
	s_addc_u32 s23, s21, -1
	s_cmpk_eq_i32 s49, 0x54
	s_cselect_b32 s25, s3, s23
	s_cselect_b32 s24, s2, s22
	s_cselect_b32 s23, s19, s48
	s_cselect_b32 s22, s18, s47
	v_lshl_add_u64 v[172:173], s[20:21], 0, v[144:145]
	s_add_i32 m0, s28, 0xc000
	ds_read_b128 v[186:189], v178
	ds_read_b128 v[190:193], v178 offset:1024
	ds_read_b128 v[194:197], v178 offset:2048
	ds_read_b128 v[198:201], v178 offset:3072
	ds_read_b128 v[202:205], v178 offset:4096
	ds_read_b128 v[206:209], v178 offset:5120
	ds_read_b128 v[210:213], v178 offset:6144
	ds_read_b128 v[214:217], v178 offset:7168
	global_load_lds_dwordx4 v[172:173], off
	v_lshl_add_u64 v[172:173], s[20:21], 0, v[146:147]
	s_add_i32 m0, s28, 0xe000
	s_nop 0
	global_load_lds_dwordx4 v[172:173], off
	s_waitcnt vmcnt(8) lgkmcnt(0)
	s_setprio 1
	s_barrier
	v_mfma_f32_16x16x32_bf16 v[124:127], v[128:131], v[186:189], v[124:127]
	v_mfma_f32_16x16x32_bf16 v[120:123], v[152:155], v[186:189], v[120:123]
	v_mfma_f32_16x16x32_bf16 v[116:119], v[128:131], v[194:197], v[116:119]
	v_mfma_f32_16x16x32_bf16 v[112:115], v[152:155], v[194:197], v[112:115]
	v_mfma_f32_16x16x32_bf16 v[108:111], v[128:131], v[202:205], v[108:111]
	v_mfma_f32_16x16x32_bf16 v[104:107], v[152:155], v[202:205], v[104:107]
	v_mfma_f32_16x16x32_bf16 v[100:103], v[128:131], v[210:213], v[100:103]
	v_mfma_f32_16x16x32_bf16 v[96:99], v[152:155], v[210:213], v[96:99]
	v_mfma_f32_16x16x32_bf16 v[124:127], v[132:135], v[190:193], v[124:127]
	v_mfma_f32_16x16x32_bf16 v[120:123], v[156:159], v[190:193], v[120:123]
	v_mfma_f32_16x16x32_bf16 v[116:119], v[132:135], v[198:201], v[116:119]
	v_mfma_f32_16x16x32_bf16 v[112:115], v[156:159], v[198:201], v[112:115]
	v_mfma_f32_16x16x32_bf16 v[108:111], v[132:135], v[206:209], v[108:111]
	v_mfma_f32_16x16x32_bf16 v[104:107], v[156:159], v[206:209], v[104:107]
	v_mfma_f32_16x16x32_bf16 v[100:103], v[132:135], v[214:217], v[100:103]
	v_mfma_f32_16x16x32_bf16 v[96:99], v[156:159], v[214:217], v[96:99]
	s_setprio 0
	s_setprio 1
	v_mfma_f32_16x16x32_bf16 v[68:71], v[160:163], v[186:189], v[68:71]
	v_mfma_f32_16x16x32_bf16 v[60:63], v[168:171], v[186:189], v[60:63]
	v_mfma_f32_16x16x32_bf16 v[52:55], v[160:163], v[194:197], v[52:55]
	v_mfma_f32_16x16x32_bf16 v[48:51], v[168:171], v[194:197], v[48:51]
	v_mfma_f32_16x16x32_bf16 v[44:47], v[160:163], v[202:205], v[44:47]
	v_mfma_f32_16x16x32_bf16 v[40:43], v[168:171], v[202:205], v[40:43]
	v_mfma_f32_16x16x32_bf16 v[36:39], v[160:163], v[210:213], v[36:39]
	v_mfma_f32_16x16x32_bf16 v[32:35], v[168:171], v[210:213], v[32:35]
	v_mfma_f32_16x16x32_bf16 v[68:71], v[164:167], v[190:193], v[68:71]
	v_mfma_f32_16x16x32_bf16 v[60:63], v[182:185], v[190:193], v[60:63]
	v_mfma_f32_16x16x32_bf16 v[52:55], v[164:167], v[198:201], v[52:55]
	v_mfma_f32_16x16x32_bf16 v[48:51], v[182:185], v[198:201], v[48:51]
	v_mfma_f32_16x16x32_bf16 v[44:47], v[164:167], v[206:209], v[44:47]
	v_mfma_f32_16x16x32_bf16 v[40:43], v[182:185], v[206:209], v[40:43]
	v_mfma_f32_16x16x32_bf16 v[36:39], v[164:167], v[214:217], v[36:39]
	v_mfma_f32_16x16x32_bf16 v[32:35], v[182:185], v[214:217], v[32:35]
	s_setprio 0
	s_barrier
	s_add_i32 s50, s40, s27
	v_lshl_add_u64 v[172:173], s[22:23], 0, v[138:139]
	s_mov_b32 m0, s50
	ds_read_b128 v[186:189], v178 offset:16384
	ds_read_b128 v[190:193], v178 offset:17408
	ds_read_b128 v[194:197], v178 offset:18432
	ds_read_b128 v[198:201], v178 offset:19456
	ds_read_b128 v[202:205], v178 offset:20480
	ds_read_b128 v[206:209], v178 offset:21504
	ds_read_b128 v[210:213], v178 offset:22528
	ds_read_b128 v[214:217], v178 offset:23552
	global_load_lds_dwordx4 v[172:173], off
	s_add_i32 m0, s50, 0x2000
	s_add_u32 s50, s22, 0x160000
	v_lshl_add_u64 v[218:219], s[22:23], 0, v[142:143]
	s_addc_u32 s51, s23, 0
	s_add_i32 s52, s41, s27
	global_load_lds_dwordx4 v[218:219], off
	v_lshl_add_u64 v[220:221], s[50:51], 0, v[138:139]
	s_mov_b32 m0, s52
	v_lshl_add_u64 v[222:223], s[24:25], 0, v[140:141]
	global_load_lds_dwordx4 v[220:221], off
	v_lshl_add_u64 v[220:221], s[50:51], 0, v[142:143]
	s_add_i32 m0, s52, 0x2000
	s_nop 0
	global_load_lds_dwordx4 v[220:221], off
	v_lshl_add_u64 v[220:221], s[24:25], 0, v[136:137]
	s_mov_b32 m0, s28
	s_nop 0
	global_load_lds_dwordx4 v[220:221], off
	s_mov_b32 m0, s29
	s_nop 0
	global_load_lds_dwordx4 v[222:223], off
	s_waitcnt vmcnt(8) lgkmcnt(0)
	s_setprio 1
	s_barrier
; #define PG8_STAGE(bufoff, gbase, voff) do { _Pragma("unroll") for (int _i = 0; _i < 2; ++_i) \
;         __builtin_amdgcn_global_load_lds((const unsigned*)((const char*)(gbase) + (voff)[_i]), (LAS unsigned*)(lds + (bufoff) + ldsw + _i * 8192), 16, 0, 0); } while (0)
; #define PG8_LDA(dst, b, h) do { _Pragma("unroll") for (int m = 0; m < 4; ++m) _Pragma("unroll") for (int k = 0; k < 2; ++k) dst[m][k] = *(const LAS bf16x8*)(lds + PG8_SA(b, h) + aoff + m * 2048 + k * 1024); } while (0)
; #define PG8_LDB(dst, b, h) do { _Pragma("unroll") for (int n = 0; n < 2; ++n) _Pragma("unroll") for (int k = 0; k < 2; ++k) dst[n][k] = *(const LAS bf16x8*)(lds + PG8_SB(b, h) + boff + n * 2048 + k * 1024); } while (0)
; #define PG8_MMA(ai, bj, At, Bt) do { __builtin_amdgcn_s_setprio(1); _Pragma("unroll") for (int m = 0; m < 4; ++m) _Pragma("unroll") for (int n = 0; n < 2; ++n) _Pragma("unroll") for (int k = 0; k < 2; ++k) \
;         acc[ai][bj][m][n] = __builtin_amdgcn_mfma_f32_16x16x32_bf16(Bt[n][k], At[m][k], acc[ai][bj][m][n], 0, 0, 0); __builtin_amdgcn_s_setprio(0); } while (0)
; #define PG8_WAIT_V(n) asm volatile("s_waitcnt vmcnt(" #n ")" ::: "memory")
; #define PG8_WAIT_L(n) asm volatile("s_waitcnt lgkmcnt(" #n ")" ::: "memory")
; #define PG8_BAR __builtin_amdgcn_s_barrier()
; #define PG8_SCHED __builtin_amdgcn_sched_barrier(0)
; template <class Epi, class Sched, bool ALIGN_EPI = false, bool SP2 = false>
; __device__ __forceinline__ void gemm_phase(LAS unsigned char* lds, const Gemm g, const Sched& S, const Epi& E) {
;     ...
;             PG8_WAIT_V(8); PG8_WAIT_L(0); PG8_BAR; PG8_MMA(1, 0, At, B0); PG8_MMA(1, 1, At, B1); PG8_BAR; PG8_SCHED;
;             PG8_LDB(B0, 1, 0); PG8_LDB(B1, 1, 1); PG8_SCHED; PG8_LDA(At, 1, 0); PG8_STAGE(PG8_SA(0, 1), a2 + hstepA, voffA);
;             PG8_WAIT_V(8); PG8_WAIT_L(0); PG8_BAR; PG8_MMA(0, 0, At, B0); PG8_MMA(0, 1, At, B1); PG8_BAR; PG8_SCHED;
	v_mfma_f32_16x16x32_bf16 v[92:95], v[128:131], v[186:189], v[92:95]
	v_mfma_f32_16x16x32_bf16 v[88:91], v[152:155], v[186:189], v[88:91]
	v_mfma_f32_16x16x32_bf16 v[84:87], v[128:131], v[194:197], v[84:87]
	v_mfma_f32_16x16x32_bf16 v[80:83], v[152:155], v[194:197], v[80:83]
	v_mfma_f32_16x16x32_bf16 v[76:79], v[128:131], v[202:205], v[76:79]
	v_mfma_f32_16x16x32_bf16 v[72:75], v[152:155], v[202:205], v[72:75]
	v_mfma_f32_16x16x32_bf16 v[64:67], v[128:131], v[210:213], v[64:67]
	v_mfma_f32_16x16x32_bf16 v[56:59], v[152:155], v[210:213], v[56:59]
	v_mfma_f32_16x16x32_bf16 v[92:95], v[132:135], v[190:193], v[92:95]
	v_mfma_f32_16x16x32_bf16 v[88:91], v[156:159], v[190:193], v[88:91]
	v_mfma_f32_16x16x32_bf16 v[84:87], v[132:135], v[198:201], v[84:87]
	v_mfma_f32_16x16x32_bf16 v[80:83], v[156:159], v[198:201], v[80:83]
	v_mfma_f32_16x16x32_bf16 v[76:79], v[132:135], v[206:209], v[76:79]
	v_mfma_f32_16x16x32_bf16 v[72:75], v[156:159], v[206:209], v[72:75]
	v_mfma_f32_16x16x32_bf16 v[64:67], v[132:135], v[214:217], v[64:67]
	v_mfma_f32_16x16x32_bf16 v[56:59], v[156:159], v[214:217], v[56:59]
	s_setprio 0
	s_setprio 1
	v_mfma_f32_16x16x32_bf16 v[28:31], v[160:163], v[186:189], v[28:31]
	v_mfma_f32_16x16x32_bf16 v[24:27], v[168:171], v[186:189], v[24:27]
	v_mfma_f32_16x16x32_bf16 v[20:23], v[160:163], v[194:197], v[20:23]
	v_mfma_f32_16x16x32_bf16 v[16:19], v[168:171], v[194:197], v[16:19]
	v_mfma_f32_16x16x32_bf16 v[12:15], v[160:163], v[202:205], v[12:15]
	v_mfma_f32_16x16x32_bf16 v[8:11], v[168:171], v[202:205], v[8:11]
	v_mfma_f32_16x16x32_bf16 v[4:7], v[160:163], v[210:213], v[4:7]
	v_mfma_f32_16x16x32_bf16 v[0:3], v[168:171], v[210:213], v[0:3]
	v_mfma_f32_16x16x32_bf16 v[28:31], v[164:167], v[190:193], v[28:31]
	v_mfma_f32_16x16x32_bf16 v[24:27], v[182:185], v[190:193], v[24:27]
	v_mfma_f32_16x16x32_bf16 v[20:23], v[164:167], v[198:201], v[20:23]
	v_mfma_f32_16x16x32_bf16 v[16:19], v[182:185], v[198:201], v[16:19]
	v_mfma_f32_16x16x32_bf16 v[12:15], v[164:167], v[206:209], v[12:15]
	v_mfma_f32_16x16x32_bf16 v[8:11], v[182:185], v[206:209], v[8:11]
	v_mfma_f32_16x16x32_bf16 v[4:7], v[164:167], v[214:217], v[4:7]
	v_mfma_f32_16x16x32_bf16 v[0:3], v[182:185], v[214:217], v[0:3]
	s_setprio 0
	s_barrier
	ds_read_b128 v[128:131], v179
	ds_read_b128 v[132:135], v179 offset:1024
	ds_read_b128 v[152:155], v179 offset:2048
	ds_read_b128 v[156:159], v179 offset:3072
	ds_read_b128 v[160:163], v180
	ds_read_b128 v[164:167], v180 offset:1024
	ds_read_b128 v[168:171], v180 offset:2048
	ds_read_b128 v[182:185], v180 offset:3072
	s_add_u32 s24, s24, 0x160000
	s_addc_u32 s25, s25, 0
	s_mov_b32 m0, s30
	v_lshl_add_u64 v[224:225], s[24:25], 0, v[136:137]
	ds_read_b128 v[186:189], v178 offset:32768
	ds_read_b128 v[190:193], v178 offset:33792
	ds_read_b128 v[194:197], v178 offset:34816
	ds_read_b128 v[198:201], v178 offset:35840
	ds_read_b128 v[202:205], v178 offset:36864
	ds_read_b128 v[206:209], v178 offset:37888
	ds_read_b128 v[210:213], v178 offset:38912
	ds_read_b128 v[214:217], v178 offset:39936
	global_load_lds_dwordx4 v[224:225], off
	v_lshl_add_u64 v[224:225], s[24:25], 0, v[140:141]
	s_mov_b32 m0, s31
	s_nop 0
	global_load_lds_dwordx4 v[224:225], off
	s_waitcnt vmcnt(8) lgkmcnt(0)
	s_setprio 1
	s_barrier
	v_mfma_f32_16x16x32_bf16 v[124:127], v[128:131], v[186:189], v[124:127]
	v_mfma_f32_16x16x32_bf16 v[120:123], v[152:155], v[186:189], v[120:123]
	v_mfma_f32_16x16x32_bf16 v[116:119], v[128:131], v[194:197], v[116:119]
	v_mfma_f32_16x16x32_bf16 v[112:115], v[152:155], v[194:197], v[112:115]
	v_mfma_f32_16x16x32_bf16 v[108:111], v[128:131], v[202:205], v[108:111]
	v_mfma_f32_16x16x32_bf16 v[104:107], v[152:155], v[202:205], v[104:107]
	v_mfma_f32_16x16x32_bf16 v[100:103], v[128:131], v[210:213], v[100:103]
	v_mfma_f32_16x16x32_bf16 v[96:99], v[152:155], v[210:213], v[96:99]
	v_mfma_f32_16x16x32_bf16 v[124:127], v[132:135], v[190:193], v[124:127]
	v_mfma_f32_16x16x32_bf16 v[120:123], v[156:159], v[190:193], v[120:123]
	v_mfma_f32_16x16x32_bf16 v[116:119], v[132:135], v[198:201], v[116:119]
	v_mfma_f32_16x16x32_bf16 v[112:115], v[156:159], v[198:201], v[112:115]
	v_mfma_f32_16x16x32_bf16 v[108:111], v[132:135], v[206:209], v[108:111]
	v_mfma_f32_16x16x32_bf16 v[104:107], v[156:159], v[206:209], v[104:107]
	v_mfma_f32_16x16x32_bf16 v[100:103], v[132:135], v[214:217], v[100:103]
	v_mfma_f32_16x16x32_bf16 v[96:99], v[156:159], v[214:217], v[96:99]
	s_setprio 0
	s_setprio 1
	v_mfma_f32_16x16x32_bf16 v[68:71], v[160:163], v[186:189], v[68:71]
	v_mfma_f32_16x16x32_bf16 v[60:63], v[168:171], v[186:189], v[60:63]
	v_mfma_f32_16x16x32_bf16 v[52:55], v[160:163], v[194:197], v[52:55]
	v_mfma_f32_16x16x32_bf16 v[48:51], v[168:171], v[194:197], v[48:51]
	v_mfma_f32_16x16x32_bf16 v[44:47], v[160:163], v[202:205], v[44:47]
	v_mfma_f32_16x16x32_bf16 v[40:43], v[168:171], v[202:205], v[40:43]
	v_mfma_f32_16x16x32_bf16 v[36:39], v[160:163], v[210:213], v[36:39]
	v_mfma_f32_16x16x32_bf16 v[32:35], v[168:171], v[210:213], v[32:35]
	v_mfma_f32_16x16x32_bf16 v[68:71], v[164:167], v[190:193], v[68:71]
	v_mfma_f32_16x16x32_bf16 v[60:63], v[182:185], v[190:193], v[60:63]
	v_mfma_f32_16x16x32_bf16 v[52:55], v[164:167], v[198:201], v[52:55]
	v_mfma_f32_16x16x32_bf16 v[48:51], v[182:185], v[198:201], v[48:51]
	v_mfma_f32_16x16x32_bf16 v[44:47], v[164:167], v[206:209], v[44:47]
	v_mfma_f32_16x16x32_bf16 v[40:43], v[182:185], v[206:209], v[40:43]
	v_mfma_f32_16x16x32_bf16 v[36:39], v[164:167], v[214:217], v[36:39]
	v_mfma_f32_16x16x32_bf16 v[32:35], v[182:185], v[214:217], v[32:35]
	s_setprio 0
	s_barrier
; #define PG8_STAGE(bufoff, gbase, voff) do { _Pragma("unroll") for (int _i = 0; _i < 2; ++_i) \
;         __builtin_amdgcn_global_load_lds((const unsigned*)((const char*)(gbase) + (voff)[_i]), (LAS unsigned*)(lds + (bufoff) + ldsw + _i * 8192), 16, 0, 0); } while (0)
; #define PG8_LDA(dst, b, h) do { _Pragma("unroll") for (int m = 0; m < 4; ++m) _Pragma("unroll") for (int k = 0; k < 2; ++k) dst[m][k] = *(const LAS bf16x8*)(lds + PG8_SA(b, h) + aoff + m * 2048 + k * 1024); } while (0)
; #define PG8_MMA(ai, bj, At, Bt) do { __builtin_amdgcn_s_setprio(1); _Pragma("unroll") for (int m = 0; m < 4; ++m) _Pragma("unroll") for (int n = 0; n < 2; ++n) _Pragma("unroll") for (int k = 0; k < 2; ++k) \
;         acc[ai][bj][m][n] = __builtin_amdgcn_mfma_f32_16x16x32_bf16(Bt[n][k], At[m][k], acc[ai][bj][m][n], 0, 0, 0); __builtin_amdgcn_s_setprio(0); } while (0)
; #define PG8_WAIT_V(n) asm volatile("s_waitcnt vmcnt(" #n ")" ::: "memory")
; #define PG8_WAIT_L(n) asm volatile("s_waitcnt lgkmcnt(" #n ")" ::: "memory")
; #define PG8_BAR __builtin_amdgcn_s_barrier()
; #define PG8_SCHED __builtin_amdgcn_sched_barrier(0)
; template <class Epi, class Sched, bool ALIGN_EPI = false, bool SP2 = false>
; __device__ __forceinline__ void gemm_phase(LAS unsigned char* lds, const Gemm g, const Sched& S, const Epi& E) {
;     ...
;             PG8_LDA(At, 1, 1); PG8_STAGE(PG8_SB(1, 0), b3, voffB); PG8_STAGE(PG8_SB(1, 1), b3 + hstepB, voffB); PG8_STAGE(PG8_SA(1, 0), a3, voffA);
;             PG8_WAIT_V(8); PG8_WAIT_L(0); PG8_BAR; PG8_MMA(1, 0, At, B0); PG8_MMA(1, 1, At, B1); PG8_BAR; PG8_SCHED;
;     ...
;         if constexpr (ALIGN_EPI) { if (wr == 0) PG8_BAR; }
	s_add_i32 s24, s42, s27
	v_lshl_add_u64 v[172:173], v[172:173], 0, s[8:9]
	s_mov_b32 m0, s24
	ds_read_b128 v[186:189], v178 offset:49152
	ds_read_b128 v[190:193], v178 offset:50176
	ds_read_b128 v[194:197], v178 offset:51200
	ds_read_b128 v[198:201], v178 offset:52224
	ds_read_b128 v[202:205], v178 offset:53248
	ds_read_b128 v[206:209], v178 offset:54272
	ds_read_b128 v[210:213], v178 offset:55296
	ds_read_b128 v[214:217], v178 offset:56320
	global_load_lds_dwordx4 v[172:173], off
	s_add_i32 m0, s24, 0x2000
	s_add_u32 s22, s22, 0x160080
	v_lshl_add_u64 v[172:173], v[218:219], 0, s[8:9]
	s_addc_u32 s23, s23, 0
	s_add_i32 s24, s43, s27
	global_load_lds_dwordx4 v[172:173], off
	v_lshl_add_u64 v[172:173], s[22:23], 0, v[138:139]
	s_mov_b32 m0, s24
	s_nop 0
	global_load_lds_dwordx4 v[172:173], off
	v_lshl_add_u64 v[172:173], s[22:23], 0, v[142:143]
	s_add_i32 m0, s24, 0x2000
	s_nop 0
	global_load_lds_dwordx4 v[172:173], off
	v_lshl_add_u64 v[172:173], v[220:221], 0, s[8:9]
	s_mov_b32 m0, s36
	s_nop 0
	global_load_lds_dwordx4 v[172:173], off
	v_lshl_add_u64 v[172:173], v[222:223], 0, s[8:9]
	s_mov_b32 m0, s37
	s_nop 0
	global_load_lds_dwordx4 v[172:173], off
	s_waitcnt vmcnt(8) lgkmcnt(0)
	s_setprio 1
	s_barrier
	v_mfma_f32_16x16x32_bf16 v[92:95], v[128:131], v[186:189], v[92:95]
	v_mfma_f32_16x16x32_bf16 v[88:91], v[152:155], v[186:189], v[88:91]
	v_mfma_f32_16x16x32_bf16 v[84:87], v[128:131], v[194:197], v[84:87]
	v_mfma_f32_16x16x32_bf16 v[80:83], v[152:155], v[194:197], v[80:83]
	v_mfma_f32_16x16x32_bf16 v[76:79], v[128:131], v[202:205], v[76:79]
	v_mfma_f32_16x16x32_bf16 v[72:75], v[152:155], v[202:205], v[72:75]
	v_mfma_f32_16x16x32_bf16 v[64:67], v[128:131], v[210:213], v[64:67]
	v_mfma_f32_16x16x32_bf16 v[56:59], v[152:155], v[210:213], v[56:59]
	v_mfma_f32_16x16x32_bf16 v[92:95], v[132:135], v[190:193], v[92:95]
	v_mfma_f32_16x16x32_bf16 v[88:91], v[156:159], v[190:193], v[88:91]
	v_mfma_f32_16x16x32_bf16 v[84:87], v[132:135], v[198:201], v[84:87]
	v_mfma_f32_16x16x32_bf16 v[80:83], v[156:159], v[198:201], v[80:83]
	v_mfma_f32_16x16x32_bf16 v[76:79], v[132:135], v[206:209], v[76:79]
	v_mfma_f32_16x16x32_bf16 v[72:75], v[156:159], v[206:209], v[72:75]
	v_mfma_f32_16x16x32_bf16 v[64:67], v[132:135], v[214:217], v[64:67]
	v_mfma_f32_16x16x32_bf16 v[56:59], v[156:159], v[214:217], v[56:59]
	s_setprio 0
	s_setprio 1
	v_mfma_f32_16x16x32_bf16 v[28:31], v[160:163], v[186:189], v[28:31]
	v_mfma_f32_16x16x32_bf16 v[24:27], v[168:171], v[186:189], v[24:27]
	v_mfma_f32_16x16x32_bf16 v[20:23], v[160:163], v[194:197], v[20:23]
	v_mfma_f32_16x16x32_bf16 v[16:19], v[168:171], v[194:197], v[16:19]
	v_mfma_f32_16x16x32_bf16 v[12:15], v[160:163], v[202:205], v[12:15]
	v_mfma_f32_16x16x32_bf16 v[8:11], v[168:171], v[202:205], v[8:11]
	v_mfma_f32_16x16x32_bf16 v[4:7], v[160:163], v[210:213], v[4:7]
	v_mfma_f32_16x16x32_bf16 v[0:3], v[168:171], v[210:213], v[0:3]
	v_mfma_f32_16x16x32_bf16 v[28:31], v[164:167], v[190:193], v[28:31]
	v_mfma_f32_16x16x32_bf16 v[24:27], v[182:185], v[190:193], v[24:27]
	v_mfma_f32_16x16x32_bf16 v[20:23], v[164:167], v[198:201], v[20:23]
	v_mfma_f32_16x16x32_bf16 v[16:19], v[182:185], v[198:201], v[16:19]
	v_mfma_f32_16x16x32_bf16 v[12:15], v[164:167], v[206:209], v[12:15]
	v_mfma_f32_16x16x32_bf16 v[8:11], v[182:185], v[206:209], v[8:11]
	v_mfma_f32_16x16x32_bf16 v[4:7], v[164:167], v[214:217], v[4:7]
	v_mfma_f32_16x16x32_bf16 v[0:3], v[182:185], v[214:217], v[0:3]
	s_add_i32 s49, s49, 2
	s_add_u32 s20, s20, 0x100
	s_addc_u32 s21, s21, 0
	s_add_u32 s47, s47, 0x100
	s_addc_u32 s48, s48, 0
	s_setprio 0
	s_barrier
	s_cmpk_gt_u32 s49, 0x55
	s_cbranch_scc0 .LBB0_1138
	s_and_b64 vcc, exec, s[10:11]
	s_cbranch_vccz .LBB0_1141
	s_barrier
